# NA step loop: two K/V staging register sets by step parity (tile loaded at step t consumed at t+2), plus rope-table load hoist
# baseline (speedup 1.0000x reference)
.LBB0_205:
	s_mul_hi_i32 s2, s46, 0x38e38e39
	s_lshr_b32 s3, s2, 31
	s_ashr_i32 s2, s2, 1
	s_add_i32 s60, s2, s3
	s_mul_i32 s2, s60, -9
	s_add_i32 s2, s2, s46
	s_lshl_b32 s2, s2, 8
	s_lshl_b32 s59, s55, 8
	s_or_b32 s58, s2, s68
	s_add_i32 s59, s59, s69
	s_cmpk_lt_i32 s59, 0x800
	s_mov_b64 s[2:3], -1
	s_cbranch_scc0 .LBB0_223
	s_cmpk_gt_i32 s58, 0xff
	s_cselect_b64 s[62:63], -1, 0
	s_add_i32 s2, s58, 0xffffff00
	s_lshr_b32 s22, s2, 2
	s_cmpk_lt_i32 s58, 0x100
	s_waitcnt lgkmcnt(5)
	v_mov_b32_e32 v134, v120
	v_mov_b32_e32 v135, v121
	s_waitcnt lgkmcnt(0)
	v_mov_b32_e32 v136, v122
	v_mov_b32_e32 v137, v123
	v_mov_b32_e32 v142, v124
	v_mov_b32_e32 v143, v125
	v_mov_b32_e32 v146, v126
	v_mov_b32_e32 v147, v127
	v_mov_b32_e32 v138, v112
	v_mov_b32_e32 v139, v113
	v_mov_b32_e32 v140, v114
	v_mov_b32_e32 v141, v115
	v_mov_b32_e32 v144, v116
	v_mov_b32_e32 v145, v117
	v_mov_b32_e32 v148, v118
	v_mov_b32_e32 v149, v119
	s_cbranch_scc1 .LBB0_208
	v_lshl_add_u64 v[142:143], s[22:23], 3, v[194:195]
	global_load_dwordx4 v[128:131], v[142:143], off offset:16
	global_load_dwordx4 v[132:135], v[142:143], off
	global_load_dwordx4 v[240:243], v[142:143], off offset:80
	global_load_dwordx4 v[244:247], v[142:143], off offset:64
	v_mov_b32_e32 v138, v120
	v_mov_b32_e32 v139, v113
	v_mov_b32_e32 v140, v112
	v_mov_b32_e32 v141, v121
	v_mov_b32_e32 v150, v124
	v_mov_b32_e32 v151, v117
	v_mov_b32_e32 v148, v116
	v_mov_b32_e32 v149, v125
	s_waitcnt vmcnt(3)
	v_mov_b32_e32 v144, v129
	s_waitcnt vmcnt(2)
	v_mov_b32_e32 v146, v132
	v_mov_b32_e32 v147, v135
	v_mov_b32_e32 v136, v133
	v_mov_b32_e32 v137, v134
	v_pk_mul_f32 v[146:147], v[138:139], v[146:147]
	v_mov_b32_e32 v138, v133
	v_mov_b32_e32 v139, v135
	v_mov_b32_e32 v133, v134
	v_pk_fma_f32 v[134:135], v[140:141], v[136:137], v[146:147]
	v_mov_b32_e32 v136, v122
	v_mov_b32_e32 v137, v115
	v_mov_b32_e32 v140, v128
	v_mov_b32_e32 v141, v131
	v_pk_mul_f32 v[138:139], v[120:121], v[138:139]
	v_pk_mul_f32 v[136:137], v[136:137], v[140:141]
	v_mov_b32_e32 v140, v129
	v_mov_b32_e32 v145, v130
	v_pk_fma_f32 v[138:139], v[112:113], v[132:133], v[138:139] neg_lo:[0,0,1] neg_hi:[0,0,1]
	v_mov_b32_e32 v132, v114
	v_mov_b32_e32 v133, v123
	v_pk_mul_f32 v[140:141], v[122:123], v[140:141]
	v_mov_b32_e32 v129, v130
	v_pk_fma_f32 v[140:141], v[114:115], v[128:129], v[140:141] neg_lo:[0,0,1] neg_hi:[0,0,1]
	v_pk_fma_f32 v[136:137], v[132:133], v[144:145], v[136:137]
	s_nop 0
	s_waitcnt vmcnt(1)
	v_mov_b32_e32 v146, v241
	s_waitcnt vmcnt(0)
	v_mov_b32_e32 v152, v244
	v_mov_b32_e32 v153, v247
	v_pk_mul_f32 v[150:151], v[150:151], v[152:153]
	v_mov_b32_e32 v152, v245
	v_mov_b32_e32 v132, v245
	v_mov_b32_e32 v133, v246
	v_pk_mul_f32 v[152:153], v[124:125], v[152:153]
	v_mov_b32_e32 v245, v246
	v_pk_fma_f32 v[246:247], v[116:117], v[244:245], v[152:153] neg_lo:[0,0,1] neg_hi:[0,0,1]
	v_pk_fma_f32 v[142:143], v[148:149], v[132:133], v[150:151]
	v_mov_b32_e32 v148, v126
	v_mov_b32_e32 v149, v119
	v_mov_b32_e32 v150, v240
	v_mov_b32_e32 v151, v243
	v_pk_mul_f32 v[150:151], v[148:149], v[150:151]
	v_mov_b32_e32 v148, v241
	v_mov_b32_e32 v149, v243
	v_mov_b32_e32 v147, v242
	v_mov_b32_e32 v132, v118
	v_mov_b32_e32 v133, v127
	v_pk_mul_f32 v[148:149], v[126:127], v[148:149]
	v_mov_b32_e32 v241, v242
	v_pk_fma_f32 v[148:149], v[118:119], v[240:241], v[148:149] neg_lo:[0,0,1] neg_hi:[0,0,1]
	v_pk_fma_f32 v[146:147], v[132:133], v[146:147], v[150:151]
	v_mov_b32_e32 v144, v246
	v_mov_b32_e32 v145, v247
.LBB0_208:
	v_cndmask_b32_e64 v128, 0, 1, s[62:63]
	v_cmp_ne_u32_e64 s[2:3], 1, v128
	s_andn2_b64 vcc, exec, s[62:63]
	v_mov_b32_e32 v150, v88
	v_mov_b32_e32 v151, v89
	v_mov_b32_e32 v152, v90
	v_mov_b32_e32 v153, v91
	v_mov_b32_e32 v158, v92
	v_mov_b32_e32 v159, v93
	v_mov_b32_e32 v128, v94
	v_mov_b32_e32 v129, v95
	v_mov_b32_e32 v154, v80
	v_mov_b32_e32 v155, v81
	v_mov_b32_e32 v156, v82
	v_mov_b32_e32 v157, v83
	v_mov_b32_e32 v160, v84
	v_mov_b32_e32 v161, v85
	v_mov_b32_e32 v130, v86
	v_mov_b32_e32 v131, v87
	s_cbranch_vccnz .LBB0_210
	global_load_dwordx4 v[128:131], v[196:197], off offset:16
	global_load_dwordx4 v[150:153], v[196:197], off
	global_load_dwordx4 v[240:243], v[196:197], off offset:80
	global_load_dwordx4 v[244:247], v[196:197], off offset:64
	v_mov_b32_e32 v154, v88
	v_mov_b32_e32 v155, v81
	v_mov_b32_e32 v156, v80
	v_mov_b32_e32 v157, v89
	v_mov_b32_e32 v166, v92
	v_mov_b32_e32 v167, v85
	v_mov_b32_e32 v164, v84
	v_mov_b32_e32 v165, v93
	s_waitcnt vmcnt(3)
	v_mov_b32_e32 v158, v129
	s_waitcnt vmcnt(2)
	v_mov_b32_e32 v160, v150
	v_mov_b32_e32 v161, v153
	v_pk_mul_f32 v[160:161], v[154:155], v[160:161]
	v_mov_b32_e32 v154, v151
	v_mov_b32_e32 v155, v153
	v_mov_b32_e32 v132, v151
	v_mov_b32_e32 v133, v152
	v_pk_mul_f32 v[154:155], v[88:89], v[154:155]
	v_mov_b32_e32 v151, v152
	v_pk_fma_f32 v[154:155], v[80:81], v[150:151], v[154:155] neg_lo:[0,0,1] neg_hi:[0,0,1]
	v_pk_fma_f32 v[150:151], v[156:157], v[132:133], v[160:161]
	v_mov_b32_e32 v152, v90
	v_mov_b32_e32 v153, v83
	v_mov_b32_e32 v156, v128
	v_mov_b32_e32 v157, v131
	v_pk_mul_f32 v[152:153], v[152:153], v[156:157]
	v_mov_b32_e32 v156, v129
	v_mov_b32_e32 v159, v130
	v_mov_b32_e32 v132, v82
	v_mov_b32_e32 v133, v91
	v_pk_mul_f32 v[156:157], v[90:91], v[156:157]
	v_mov_b32_e32 v129, v130
	v_pk_fma_f32 v[156:157], v[82:83], v[128:129], v[156:157] neg_lo:[0,0,1] neg_hi:[0,0,1]
	v_pk_fma_f32 v[152:153], v[132:133], v[158:159], v[152:153]
	s_waitcnt vmcnt(1)
	v_mov_b32_e32 v162, v241
	s_waitcnt vmcnt(0)
	v_mov_b32_e32 v168, v244
	v_mov_b32_e32 v169, v247
	v_pk_mul_f32 v[166:167], v[166:167], v[168:169]
	v_mov_b32_e32 v168, v245
	v_mov_b32_e32 v132, v245
	v_mov_b32_e32 v133, v246
	v_pk_mul_f32 v[168:169], v[92:93], v[168:169]
	v_mov_b32_e32 v245, v246
	v_pk_fma_f32 v[246:247], v[84:85], v[244:245], v[168:169] neg_lo:[0,0,1] neg_hi:[0,0,1]
	v_pk_fma_f32 v[158:159], v[164:165], v[132:133], v[166:167]
	v_mov_b32_e32 v164, v94
	v_mov_b32_e32 v165, v87
	v_mov_b32_e32 v166, v240
	v_mov_b32_e32 v167, v243
	v_pk_mul_f32 v[164:165], v[164:165], v[166:167]
	v_mov_b32_e32 v166, v241
	v_mov_b32_e32 v163, v242
	v_mov_b32_e32 v132, v86
	v_mov_b32_e32 v133, v95
	v_pk_mul_f32 v[166:167], v[94:95], v[166:167]
	v_mov_b32_e32 v241, v242
	v_pk_fma_f32 v[242:243], v[86:87], v[240:241], v[166:167] neg_lo:[0,0,1] neg_hi:[0,0,1]
	v_pk_fma_f32 v[128:129], v[132:133], v[162:163], v[164:165]
	v_mov_b32_e32 v130, v242
	v_mov_b32_e32 v131, v243
	v_mov_b32_e32 v160, v246
	v_mov_b32_e32 v161, v247
.LBB0_210:
	s_and_b32 s61, s59, 0x380
	s_cmpk_lt_u32 s59, 0x400
	s_cselect_b64 vcc, -1, 0
	v_cndmask_b32_e32 v132, 1.0, v219, vcc
	v_pk_mul_f32 v[138:139], v[132:133], v[138:139] op_sel_hi:[0,1]
	v_pk_mul_f32 v[140:141], v[132:133], v[140:141] op_sel_hi:[0,1]
	v_pk_mul_f32 v[134:135], v[132:133], v[134:135] op_sel_hi:[0,1]
	v_pk_mul_f32 v[136:137], v[132:133], v[136:137] op_sel_hi:[0,1]
	v_readlane_b32 s80, v239, 32
	v_cvt_pk_bf16_f32 v138, v138, v139
	v_cvt_pk_bf16_f32 v139, v140, v141
	v_pk_mul_f32 v[140:141], v[132:133], v[144:145] op_sel_hi:[0,1]
	v_pk_mul_f32 v[144:145], v[132:133], v[148:149] op_sel_hi:[0,1]
	v_cvt_pk_bf16_f32 v134, v134, v135
	v_cvt_pk_bf16_f32 v135, v136, v137
	v_pk_mul_f32 v[136:137], v[132:133], v[142:143] op_sel_hi:[0,1]
	v_pk_mul_f32 v[142:143], v[132:133], v[146:147] op_sel_hi:[0,1]
	s_and_b64 s[62:63], vcc, exec
	v_readlane_b32 s82, v239, 34
	v_readlane_b32 s83, v239, 35
	v_readlane_b32 s84, v239, 36
	v_readlane_b32 s85, v239, 37
	v_cvt_pk_bf16_f32 v140, v140, v141
	v_cvt_pk_bf16_f32 v141, v144, v145
	v_cvt_pk_bf16_f32 v136, v136, v137
	v_cvt_pk_bf16_f32 v137, v142, v143
	s_cselect_b32 vcc_lo, s83, s85
	s_cselect_b32 vcc_hi, s82, s84
	s_mul_i32 s62, s60, 0x900
	s_ashr_i32 s52, s58, 31
	v_pk_mul_f32 v[142:143], v[132:133], v[154:155] op_sel_hi:[0,1]
	v_pk_mul_f32 v[144:145], v[132:133], v[156:157] op_sel_hi:[0,1]
	s_mul_hi_i32 s63, s60, 0x900
	s_add_u32 s62, s62, s58
	v_cvt_pk_bf16_f32 v142, v142, v143
	v_cvt_pk_bf16_f32 v143, v144, v145
	v_pk_mul_f32 v[144:145], v[132:133], v[160:161] op_sel_hi:[0,1]
	v_pk_mul_f32 v[130:131], v[132:133], v[130:131] op_sel_hi:[0,1]
	s_addc_u32 s63, s63, s52
	v_cvt_pk_bf16_f32 v144, v144, v145
	v_cvt_pk_bf16_f32 v145, v130, v131
	v_pk_mul_f32 v[130:131], v[132:133], v[150:151] op_sel_hi:[0,1]
	v_pk_mul_f32 v[146:147], v[132:133], v[152:153] op_sel_hi:[0,1]
	s_lshl_b64 s[62:63], s[62:63], 11
	v_cvt_pk_bf16_f32 v130, v130, v131
	v_cvt_pk_bf16_f32 v131, v146, v147
	v_pk_mul_f32 v[146:147], v[132:133], v[158:159] op_sel_hi:[0,1]
	v_pk_mul_f32 v[128:129], v[132:133], v[128:129] op_sel_hi:[0,1]
	s_add_u32 s52, vcc_hi, s62
	v_cvt_pk_bf16_f32 v146, v146, v147
	v_cvt_pk_bf16_f32 v147, v128, v129
	ds_write2_b64 v220, v[138:139], v[140:141] offset1:2
	ds_write2_b64 v220, v[134:135], v[136:137] offset0:4 offset1:6
	ds_write2_b64 v220, v[142:143], v[144:145] offset0:8 offset1:10
	ds_write2_b64 v220, v[130:131], v[146:147] offset0:12 offset1:14
	s_addc_u32 s63, vcc_lo, s63
	s_lshl_b32 s61, s61, 1
	ds_read2_b64 v[128:131], v221 offset1:1
	ds_read2_b64 v[140:143], v222 offset1:1
	s_add_u32 s62, s52, s61
	s_addc_u32 s63, s63, 0
	v_lshl_add_u64 v[134:135], s[62:63], 0, v[178:179]
	v_lshl_add_u64 v[136:137], v[134:135], 0, v[186:187]
	s_waitcnt lgkmcnt(1)
	global_store_dwordx4 v[136:137], v[128:131], off
	ds_read2_b64 v[128:131], v223 offset1:1
	ds_read2_b64 v[144:147], v224 offset1:1
	v_lshl_add_u64 v[138:139], v[134:135], 0, v[188:189]
	s_waitcnt lgkmcnt(2)
	global_store_dwordx4 v[138:139], v[140:143], off
	v_readlane_b32 s81, v239, 33
	v_readlane_b32 s86, v239, 38
	v_lshl_add_u64 v[140:141], v[134:135], 0, v[190:191]
	v_lshl_add_u64 v[142:143], v[134:135], 0, v[192:193]
	v_readlane_b32 s87, v239, 39
	s_waitcnt lgkmcnt(1)
	global_store_dwordx4 v[140:141], v[128:131], off
	s_waitcnt lgkmcnt(0)
	global_store_dwordx4 v[142:143], v[144:147], off
	s_and_b64 vcc, exec, s[2:3]
	s_nop 0
	v_mov_b32_e32 v144, v56
	v_mov_b32_e32 v145, v57
	v_mov_b32_e32 v146, v58
	v_mov_b32_e32 v147, v59
	v_mov_b32_e32 v152, v60
	v_mov_b32_e32 v153, v61
	v_mov_b32_e32 v156, v62
	v_mov_b32_e32 v157, v63
	v_mov_b32_e32 v148, v48
	v_mov_b32_e32 v149, v49
	v_mov_b32_e32 v150, v50
	v_mov_b32_e32 v151, v51
	v_mov_b32_e32 v154, v52
	v_mov_b32_e32 v155, v53
	v_mov_b32_e32 v158, v54
	v_mov_b32_e32 v159, v55
	s_cbranch_vccnz .LBB0_212
	v_lshl_add_u64 v[152:153], s[22:23], 3, v[194:195]
	global_load_dwordx4 v[128:131], v[152:153], off offset:16
	global_load_dwordx4 v[144:147], v[152:153], off
	global_load_dwordx4 v[240:243], v[152:153], off offset:80
	global_load_dwordx4 v[244:247], v[152:153], off offset:64
	v_mov_b32_e32 v148, v56
	v_mov_b32_e32 v149, v49
	v_mov_b32_e32 v156, v48
	v_mov_b32_e32 v157, v57
	v_mov_b32_e32 v162, v60
	v_mov_b32_e32 v163, v53
	s_waitcnt vmcnt(3)
	v_mov_b32_e32 v154, v129
	s_waitcnt vmcnt(2)
	v_mov_b32_e32 v158, v144
	v_mov_b32_e32 v159, v147
	v_pk_mul_f32 v[158:159], v[148:149], v[158:159]
	v_mov_b32_e32 v148, v145
	v_mov_b32_e32 v149, v147
	v_mov_b32_e32 v150, v145
	v_mov_b32_e32 v151, v146
	v_pk_mul_f32 v[148:149], v[56:57], v[148:149]
	v_mov_b32_e32 v145, v146
	v_pk_fma_f32 v[148:149], v[48:49], v[144:145], v[148:149] neg_lo:[0,0,1] neg_hi:[0,0,1]
	v_pk_fma_f32 v[144:145], v[156:157], v[150:151], v[158:159]
	v_mov_b32_e32 v150, v58
	v_mov_b32_e32 v151, v51
	v_mov_b32_e32 v156, v128
	v_mov_b32_e32 v157, v131
	v_pk_mul_f32 v[156:157], v[150:151], v[156:157]
	v_mov_b32_e32 v150, v129
	v_mov_b32_e32 v151, v131
	v_mov_b32_e32 v155, v130
	v_mov_b32_e32 v146, v50
	v_mov_b32_e32 v147, v59
	v_pk_mul_f32 v[150:151], v[58:59], v[150:151]
	v_mov_b32_e32 v129, v130
	v_pk_fma_f32 v[150:151], v[50:51], v[128:129], v[150:151] neg_lo:[0,0,1] neg_hi:[0,0,1]
	v_pk_fma_f32 v[146:147], v[146:147], v[154:155], v[156:157]
	s_nop 0
	v_mov_b32_e32 v158, v52
	v_mov_b32_e32 v159, v61
	s_waitcnt vmcnt(1)
	v_mov_b32_e32 v160, v241
	s_waitcnt vmcnt(0)
	v_mov_b32_e32 v164, v244
	v_mov_b32_e32 v165, v247
	v_pk_mul_f32 v[162:163], v[162:163], v[164:165]
	v_mov_b32_e32 v164, v245
	v_mov_b32_e32 v156, v245
	v_mov_b32_e32 v157, v246
	v_pk_mul_f32 v[164:165], v[60:61], v[164:165]
	v_mov_b32_e32 v245, v246
	v_pk_fma_f32 v[246:247], v[52:53], v[244:245], v[164:165] neg_lo:[0,0,1] neg_hi:[0,0,1]
	v_pk_fma_f32 v[152:153], v[158:159], v[156:157], v[162:163]
	v_mov_b32_e32 v158, v62
	v_mov_b32_e32 v159, v55
	v_mov_b32_e32 v162, v240
	v_mov_b32_e32 v163, v243
	v_pk_mul_f32 v[162:163], v[158:159], v[162:163]
	v_mov_b32_e32 v158, v241
	v_mov_b32_e32 v159, v243
	v_mov_b32_e32 v161, v242
	v_mov_b32_e32 v156, v54
	v_mov_b32_e32 v157, v63
	v_pk_mul_f32 v[158:159], v[62:63], v[158:159]
	v_mov_b32_e32 v241, v242
	v_pk_fma_f32 v[158:159], v[54:55], v[240:241], v[158:159] neg_lo:[0,0,1] neg_hi:[0,0,1]
	v_pk_fma_f32 v[156:157], v[156:157], v[160:161], v[162:163]
	v_mov_b32_e32 v154, v246
	v_mov_b32_e32 v155, v247
.LBB0_212:
	s_and_b64 vcc, exec, s[2:3]
	v_mov_b32_e32 v160, v24
	v_mov_b32_e32 v161, v25
	v_mov_b32_e32 v162, v26
	v_mov_b32_e32 v163, v27
	v_mov_b32_e32 v168, v28
	v_mov_b32_e32 v169, v29
	v_mov_b32_e32 v128, v30
	v_mov_b32_e32 v129, v31
	v_mov_b32_e32 v164, v16
	v_mov_b32_e32 v165, v17
	v_mov_b32_e32 v166, v18
	v_mov_b32_e32 v167, v19
	v_mov_b32_e32 v170, v20
	v_mov_b32_e32 v171, v21
	v_mov_b32_e32 v130, v22
	v_mov_b32_e32 v131, v23
	s_cbranch_vccnz .LBB0_214
	global_load_dwordx4 v[128:131], v[196:197], off offset:16
	global_load_dwordx4 v[160:163], v[196:197], off
	global_load_dwordx4 v[240:243], v[196:197], off offset:80
	global_load_dwordx4 v[244:247], v[196:197], off offset:64
	v_mov_b32_e32 v164, v24
	v_mov_b32_e32 v165, v17
	v_mov_b32_e32 v170, v16
	v_mov_b32_e32 v171, v25
	v_mov_b32_e32 v228, v28
	v_mov_b32_e32 v229, v21
	v_mov_b32_e32 v226, v20
	v_mov_b32_e32 v227, v29
	s_waitcnt vmcnt(3)
	v_mov_b32_e32 v168, v129
	s_waitcnt vmcnt(2)
	v_mov_b32_e32 v172, v160
	v_mov_b32_e32 v173, v163
	v_pk_mul_f32 v[172:173], v[164:165], v[172:173]
	v_mov_b32_e32 v164, v161
	v_mov_b32_e32 v165, v163
	v_mov_b32_e32 v166, v161
	v_mov_b32_e32 v167, v162
	v_pk_mul_f32 v[164:165], v[24:25], v[164:165]
	v_mov_b32_e32 v161, v162
	v_pk_fma_f32 v[164:165], v[16:17], v[160:161], v[164:165] neg_lo:[0,0,1] neg_hi:[0,0,1]
	v_pk_fma_f32 v[160:161], v[170:171], v[166:167], v[172:173]
	v_mov_b32_e32 v166, v26
	v_mov_b32_e32 v167, v19
	v_mov_b32_e32 v170, v128
	v_mov_b32_e32 v171, v131
	v_pk_mul_f32 v[170:171], v[166:167], v[170:171]
	v_mov_b32_e32 v166, v129
	v_mov_b32_e32 v167, v131
	v_mov_b32_e32 v169, v130
	v_mov_b32_e32 v162, v18
	v_mov_b32_e32 v163, v27
	v_pk_mul_f32 v[166:167], v[26:27], v[166:167]
	v_mov_b32_e32 v129, v130
	v_pk_fma_f32 v[166:167], v[18:19], v[128:129], v[166:167] neg_lo:[0,0,1] neg_hi:[0,0,1]
	v_pk_fma_f32 v[162:163], v[162:163], v[168:169], v[170:171]
	s_waitcnt vmcnt(1)
	v_mov_b32_e32 v174, v241
	s_waitcnt vmcnt(0)
	v_mov_b32_e32 v230, v244
	v_mov_b32_e32 v231, v247
	v_pk_mul_f32 v[228:229], v[228:229], v[230:231]
	v_mov_b32_e32 v230, v245
	v_mov_b32_e32 v172, v245
	v_mov_b32_e32 v173, v246
	v_pk_mul_f32 v[230:231], v[28:29], v[230:231]
	v_mov_b32_e32 v245, v246
	v_pk_fma_f32 v[246:247], v[20:21], v[244:245], v[230:231] neg_lo:[0,0,1] neg_hi:[0,0,1]
	v_pk_fma_f32 v[168:169], v[226:227], v[172:173], v[228:229]
	v_mov_b32_e32 v226, v30
	v_mov_b32_e32 v227, v23
	v_mov_b32_e32 v228, v240
	v_mov_b32_e32 v229, v243
	v_pk_mul_f32 v[226:227], v[226:227], v[228:229]
	v_mov_b32_e32 v228, v241
	v_mov_b32_e32 v175, v242
	v_mov_b32_e32 v172, v22
	v_mov_b32_e32 v173, v31
	v_pk_mul_f32 v[228:229], v[30:31], v[228:229]
	v_mov_b32_e32 v241, v242
	v_pk_fma_f32 v[242:243], v[22:23], v[240:241], v[228:229] neg_lo:[0,0,1] neg_hi:[0,0,1]
	v_pk_fma_f32 v[128:129], v[172:173], v[174:175], v[226:227]
	v_mov_b32_e32 v130, v242
	v_mov_b32_e32 v131, v243
	v_mov_b32_e32 v170, v246
	v_mov_b32_e32 v171, v247
.LBB0_214:
	v_mov_b32_e32 v133, v132
	v_pk_mul_f32 v[148:149], v[132:133], v[148:149]
	v_pk_mul_f32 v[150:151], v[132:133], v[150:151]
	v_pk_mul_f32 v[144:145], v[132:133], v[144:145]
	v_pk_mul_f32 v[146:147], v[132:133], v[146:147]
	v_cvt_pk_bf16_f32 v148, v148, v149
	v_cvt_pk_bf16_f32 v149, v150, v151
	v_pk_mul_f32 v[150:151], v[132:133], v[154:155]
	v_pk_mul_f32 v[154:155], v[132:133], v[158:159]
	v_cvt_pk_bf16_f32 v144, v144, v145
	v_cvt_pk_bf16_f32 v145, v146, v147
	v_pk_mul_f32 v[146:147], v[132:133], v[152:153]
	v_pk_mul_f32 v[152:153], v[132:133], v[156:157]
	v_cvt_pk_bf16_f32 v150, v150, v151
	v_cvt_pk_bf16_f32 v151, v154, v155
	v_cvt_pk_bf16_f32 v146, v146, v147
	v_cvt_pk_bf16_f32 v147, v152, v153
	v_pk_mul_f32 v[152:153], v[132:133], v[164:165]
	v_pk_mul_f32 v[154:155], v[132:133], v[166:167]
	v_cvt_pk_bf16_f32 v152, v152, v153
	v_cvt_pk_bf16_f32 v153, v154, v155
	v_pk_mul_f32 v[154:155], v[132:133], v[170:171]
	v_pk_mul_f32 v[130:131], v[132:133], v[130:131]
	v_cvt_pk_bf16_f32 v154, v154, v155
	v_cvt_pk_bf16_f32 v155, v130, v131
	v_pk_mul_f32 v[130:131], v[132:133], v[160:161]
	v_pk_mul_f32 v[156:157], v[132:133], v[162:163]
	v_cvt_pk_bf16_f32 v130, v130, v131
	v_cvt_pk_bf16_f32 v131, v156, v157
	v_pk_mul_f32 v[156:157], v[132:133], v[168:169]
	v_pk_mul_f32 v[128:129], v[132:133], v[128:129]
	v_cvt_pk_bf16_f32 v156, v156, v157
	v_cvt_pk_bf16_f32 v157, v128, v129
	ds_write2_b64 v220, v[148:149], v[150:151] offset1:2
	ds_write2_b64 v220, v[144:145], v[146:147] offset0:4 offset1:6
	ds_write2_b64 v220, v[152:153], v[154:155] offset0:8 offset1:10
	ds_write2_b64 v220, v[130:131], v[156:157] offset0:12 offset1:14
	ds_read2_b64 v[128:131], v221 offset1:1
	ds_read2_b64 v[144:147], v222 offset1:1
	ds_read2_b64 v[148:151], v223 offset1:1
	ds_read2_b64 v[152:155], v224 offset1:1
	s_waitcnt lgkmcnt(3)
	global_store_dwordx4 v[136:137], v[128:131], off offset:128
	s_waitcnt lgkmcnt(2)
	global_store_dwordx4 v[138:139], v[144:147], off offset:128
	s_waitcnt lgkmcnt(1)
	global_store_dwordx4 v[140:141], v[148:151], off offset:128
	s_waitcnt lgkmcnt(0)
	global_store_dwordx4 v[142:143], v[152:155], off offset:128
	s_and_b64 vcc, exec, s[2:3]
	v_mov_b32_e32 v136, v104
	v_mov_b32_e32 v137, v105
	v_mov_b32_e32 v138, v106
	v_mov_b32_e32 v139, v107
	v_mov_b32_e32 v144, v108
	v_mov_b32_e32 v145, v109
	v_mov_b32_e32 v148, v110
	v_mov_b32_e32 v149, v111
	v_mov_b32_e32 v140, v96
	v_mov_b32_e32 v141, v97
	v_mov_b32_e32 v142, v98
	v_mov_b32_e32 v143, v99
	v_mov_b32_e32 v146, v100
	v_mov_b32_e32 v147, v101
	v_mov_b32_e32 v150, v102
	v_mov_b32_e32 v151, v103
	s_cbranch_vccnz .LBB0_216
	v_lshl_add_u64 v[144:145], s[22:23], 3, v[194:195]
	global_load_dwordx4 v[128:131], v[144:145], off offset:16
	global_load_dwordx4 v[136:139], v[144:145], off
	global_load_dwordx4 v[240:243], v[144:145], off offset:80
	global_load_dwordx4 v[244:247], v[144:145], off offset:64
	v_mov_b32_e32 v140, v104
	v_mov_b32_e32 v141, v97
	v_mov_b32_e32 v148, v96
	v_mov_b32_e32 v149, v105
	v_mov_b32_e32 v154, v108
	v_mov_b32_e32 v155, v101
	s_waitcnt vmcnt(3)
	v_mov_b32_e32 v146, v129
	s_waitcnt vmcnt(2)
	v_mov_b32_e32 v150, v136
	v_mov_b32_e32 v151, v139
	v_pk_mul_f32 v[150:151], v[140:141], v[150:151]
	v_mov_b32_e32 v140, v137
	v_mov_b32_e32 v141, v139
	v_mov_b32_e32 v142, v137
	v_mov_b32_e32 v143, v138
	v_pk_mul_f32 v[140:141], v[104:105], v[140:141]
	v_mov_b32_e32 v137, v138
	v_pk_fma_f32 v[140:141], v[96:97], v[136:137], v[140:141] neg_lo:[0,0,1] neg_hi:[0,0,1]
	v_pk_fma_f32 v[136:137], v[148:149], v[142:143], v[150:151]
	v_mov_b32_e32 v142, v106
	v_mov_b32_e32 v143, v99
	v_mov_b32_e32 v148, v128
	v_mov_b32_e32 v149, v131
	v_pk_mul_f32 v[148:149], v[142:143], v[148:149]
	v_mov_b32_e32 v142, v129
	v_mov_b32_e32 v143, v131
	v_mov_b32_e32 v147, v130
	v_mov_b32_e32 v138, v98
	v_mov_b32_e32 v139, v107
	v_pk_mul_f32 v[142:143], v[106:107], v[142:143]
	v_mov_b32_e32 v129, v130
	v_pk_fma_f32 v[142:143], v[98:99], v[128:129], v[142:143] neg_lo:[0,0,1] neg_hi:[0,0,1]
	v_pk_fma_f32 v[138:139], v[138:139], v[146:147], v[148:149]
	s_nop 0
	v_mov_b32_e32 v150, v100
	v_mov_b32_e32 v151, v109
	s_waitcnt vmcnt(1)
	v_mov_b32_e32 v152, v241
	s_waitcnt vmcnt(0)
	v_mov_b32_e32 v156, v244
	v_mov_b32_e32 v157, v247
	v_pk_mul_f32 v[154:155], v[154:155], v[156:157]
	v_mov_b32_e32 v156, v245
	v_mov_b32_e32 v148, v245
	v_mov_b32_e32 v149, v246
	v_pk_mul_f32 v[156:157], v[108:109], v[156:157]
	v_mov_b32_e32 v245, v246
	v_pk_fma_f32 v[246:247], v[100:101], v[244:245], v[156:157] neg_lo:[0,0,1] neg_hi:[0,0,1]
	v_pk_fma_f32 v[144:145], v[150:151], v[148:149], v[154:155]
	v_mov_b32_e32 v150, v110
	v_mov_b32_e32 v151, v103
	v_mov_b32_e32 v154, v240
	v_mov_b32_e32 v155, v243
	v_pk_mul_f32 v[154:155], v[150:151], v[154:155]
	v_mov_b32_e32 v150, v241
	v_mov_b32_e32 v151, v243
	v_mov_b32_e32 v153, v242
	v_mov_b32_e32 v148, v102
	v_mov_b32_e32 v149, v111
	v_pk_mul_f32 v[150:151], v[110:111], v[150:151]
	v_mov_b32_e32 v241, v242
	v_pk_fma_f32 v[150:151], v[102:103], v[240:241], v[150:151] neg_lo:[0,0,1] neg_hi:[0,0,1]
	v_pk_fma_f32 v[148:149], v[148:149], v[152:153], v[154:155]
	v_mov_b32_e32 v146, v246
	v_mov_b32_e32 v147, v247
.LBB0_216:
	s_and_b64 vcc, exec, s[2:3]
	v_mov_b32_e32 v152, v72
	v_mov_b32_e32 v153, v73
	v_mov_b32_e32 v154, v74
	v_mov_b32_e32 v155, v75
	v_mov_b32_e32 v160, v76
	v_mov_b32_e32 v161, v77
	v_mov_b32_e32 v128, v78
	v_mov_b32_e32 v129, v79
	v_mov_b32_e32 v156, v64
	v_mov_b32_e32 v157, v65
	v_mov_b32_e32 v158, v66
	v_mov_b32_e32 v159, v67
	v_mov_b32_e32 v162, v68
	v_mov_b32_e32 v163, v69
	v_mov_b32_e32 v130, v70
	v_mov_b32_e32 v131, v71
	s_cbranch_vccnz .LBB0_218
	global_load_dwordx4 v[128:131], v[198:199], off offset:16
	global_load_dwordx4 v[152:155], v[198:199], off
	global_load_dwordx4 v[240:243], v[198:199], off offset:80
	global_load_dwordx4 v[244:247], v[198:199], off offset:64
	v_mov_b32_e32 v156, v72
	v_mov_b32_e32 v157, v65
	v_mov_b32_e32 v162, v64
	v_mov_b32_e32 v163, v73
	v_mov_b32_e32 v170, v76
	v_mov_b32_e32 v171, v69
	v_mov_b32_e32 v168, v68
	v_mov_b32_e32 v169, v77
	s_waitcnt vmcnt(3)
	v_mov_b32_e32 v160, v129
	s_waitcnt vmcnt(2)
	v_mov_b32_e32 v164, v152
	v_mov_b32_e32 v165, v155
	v_pk_mul_f32 v[164:165], v[156:157], v[164:165]
	v_mov_b32_e32 v156, v153
	v_mov_b32_e32 v157, v155
	v_mov_b32_e32 v158, v153
	v_mov_b32_e32 v159, v154
	v_pk_mul_f32 v[156:157], v[72:73], v[156:157]
	v_mov_b32_e32 v153, v154
	v_pk_fma_f32 v[156:157], v[64:65], v[152:153], v[156:157] neg_lo:[0,0,1] neg_hi:[0,0,1]
	v_pk_fma_f32 v[152:153], v[162:163], v[158:159], v[164:165]
	v_mov_b32_e32 v158, v74
	v_mov_b32_e32 v159, v67
	v_mov_b32_e32 v162, v128
	v_mov_b32_e32 v163, v131
	v_pk_mul_f32 v[162:163], v[158:159], v[162:163]
	v_mov_b32_e32 v158, v129
	v_mov_b32_e32 v159, v131
	v_mov_b32_e32 v161, v130
	v_mov_b32_e32 v154, v66
	v_mov_b32_e32 v155, v75
	v_pk_mul_f32 v[158:159], v[74:75], v[158:159]
	v_mov_b32_e32 v129, v130
	v_pk_fma_f32 v[158:159], v[66:67], v[128:129], v[158:159] neg_lo:[0,0,1] neg_hi:[0,0,1]
	v_pk_fma_f32 v[154:155], v[154:155], v[160:161], v[162:163]
	s_waitcnt vmcnt(1)
	v_mov_b32_e32 v166, v241
	s_waitcnt vmcnt(0)
	v_mov_b32_e32 v172, v244
	v_mov_b32_e32 v173, v247
	v_pk_mul_f32 v[170:171], v[170:171], v[172:173]
	v_mov_b32_e32 v172, v245
	v_mov_b32_e32 v164, v245
	v_mov_b32_e32 v165, v246
	v_pk_mul_f32 v[172:173], v[76:77], v[172:173]
	v_mov_b32_e32 v245, v246
	v_pk_fma_f32 v[246:247], v[68:69], v[244:245], v[172:173] neg_lo:[0,0,1] neg_hi:[0,0,1]
	v_pk_fma_f32 v[160:161], v[168:169], v[164:165], v[170:171]
	v_mov_b32_e32 v168, v78
	v_mov_b32_e32 v169, v71
	v_mov_b32_e32 v170, v240
	v_mov_b32_e32 v171, v243
	v_pk_mul_f32 v[168:169], v[168:169], v[170:171]
	v_mov_b32_e32 v170, v241
	v_mov_b32_e32 v167, v242
	v_mov_b32_e32 v164, v70
	v_mov_b32_e32 v165, v79
	v_pk_mul_f32 v[170:171], v[78:79], v[170:171]
	v_mov_b32_e32 v241, v242
	v_pk_fma_f32 v[242:243], v[70:71], v[240:241], v[170:171] neg_lo:[0,0,1] neg_hi:[0,0,1]
	v_pk_fma_f32 v[128:129], v[164:165], v[166:167], v[168:169]
	v_mov_b32_e32 v130, v242
	v_mov_b32_e32 v131, v243
	v_mov_b32_e32 v162, v246
	v_mov_b32_e32 v163, v247
.LBB0_218:
	v_pk_mul_f32 v[140:141], v[132:133], v[140:141]
	v_pk_mul_f32 v[142:143], v[132:133], v[142:143]
	v_pk_mul_f32 v[136:137], v[132:133], v[136:137]
	v_pk_mul_f32 v[138:139], v[132:133], v[138:139]
	v_cvt_pk_bf16_f32 v140, v140, v141
	v_cvt_pk_bf16_f32 v141, v142, v143
	v_pk_mul_f32 v[142:143], v[132:133], v[146:147]
	v_pk_mul_f32 v[146:147], v[132:133], v[150:151]
	v_cvt_pk_bf16_f32 v136, v136, v137
	v_cvt_pk_bf16_f32 v137, v138, v139
	v_pk_mul_f32 v[138:139], v[132:133], v[144:145]
	v_pk_mul_f32 v[144:145], v[132:133], v[148:149]
	v_cvt_pk_bf16_f32 v142, v142, v143
	v_cvt_pk_bf16_f32 v143, v146, v147
	v_cvt_pk_bf16_f32 v138, v138, v139
	v_cvt_pk_bf16_f32 v139, v144, v145
	v_pk_mul_f32 v[144:145], v[132:133], v[156:157]
	v_pk_mul_f32 v[146:147], v[132:133], v[158:159]
	v_cvt_pk_bf16_f32 v144, v144, v145
	v_cvt_pk_bf16_f32 v145, v146, v147
	v_pk_mul_f32 v[146:147], v[132:133], v[162:163]
	v_pk_mul_f32 v[130:131], v[132:133], v[130:131]
	v_cvt_pk_bf16_f32 v146, v146, v147
	v_cvt_pk_bf16_f32 v147, v130, v131
	v_pk_mul_f32 v[130:131], v[132:133], v[152:153]
	v_pk_mul_f32 v[148:149], v[132:133], v[154:155]
	v_cvt_pk_bf16_f32 v130, v130, v131
	v_cvt_pk_bf16_f32 v131, v148, v149
	v_pk_mul_f32 v[148:149], v[132:133], v[160:161]
	v_pk_mul_f32 v[128:129], v[132:133], v[128:129]
	v_cvt_pk_bf16_f32 v148, v148, v149
	v_cvt_pk_bf16_f32 v149, v128, v129
	ds_write2_b64 v220, v[140:141], v[142:143] offset1:2
	ds_write2_b64 v220, v[136:137], v[138:139] offset0:4 offset1:6
	ds_write2_b64 v220, v[144:145], v[146:147] offset0:8 offset1:10
	ds_write2_b64 v220, v[130:131], v[148:149] offset0:12 offset1:14
	ds_read2_b64 v[128:131], v221 offset1:1
	ds_read2_b64 v[136:139], v222 offset1:1
	s_mov_b64 s[62:63], 0x10000
	v_lshl_add_u64 v[144:145], v[134:135], 0, s[62:63]
	v_lshl_add_u64 v[140:141], v[144:145], 0, v[186:187]
	s_waitcnt lgkmcnt(1)
	global_store_dwordx4 v[140:141], v[128:131], off
	ds_read2_b64 v[128:131], v223 offset1:1
	ds_read2_b64 v[140:143], v224 offset1:1
	v_lshl_add_u64 v[146:147], v[144:145], 0, v[188:189]
	s_waitcnt lgkmcnt(2)
	global_store_dwordx4 v[146:147], v[136:139], off
	s_nop 1
	v_lshl_add_u64 v[136:137], v[144:145], 0, v[190:191]
	s_waitcnt lgkmcnt(1)
	global_store_dwordx4 v[136:137], v[128:131], off
	s_nop 1
	v_lshl_add_u64 v[128:129], v[144:145], 0, v[192:193]
	s_waitcnt lgkmcnt(0)
	global_store_dwordx4 v[128:129], v[140:143], off
	s_and_b64 vcc, exec, s[2:3]
	v_mov_b32_e32 v136, v40
	v_mov_b32_e32 v137, v41
	v_mov_b32_e32 v138, v42
	v_mov_b32_e32 v139, v43
	v_mov_b32_e32 v144, v44
	v_mov_b32_e32 v145, v45
	v_mov_b32_e32 v148, v46
	v_mov_b32_e32 v149, v47
	v_mov_b32_e32 v140, v32
	v_mov_b32_e32 v141, v33
	v_mov_b32_e32 v142, v34
	v_mov_b32_e32 v143, v35
	v_mov_b32_e32 v146, v36
	v_mov_b32_e32 v147, v37
	v_mov_b32_e32 v150, v38
	v_mov_b32_e32 v151, v39
	s_cbranch_vccnz .LBB0_220
	v_lshl_add_u64 v[144:145], s[22:23], 3, v[194:195]
	global_load_dwordx4 v[128:131], v[144:145], off offset:16
	global_load_dwordx4 v[136:139], v[144:145], off
	global_load_dwordx4 v[240:243], v[144:145], off offset:80
	global_load_dwordx4 v[244:247], v[144:145], off offset:64
	v_mov_b32_e32 v140, v40
	v_mov_b32_e32 v141, v33
	v_mov_b32_e32 v148, v32
	v_mov_b32_e32 v149, v41
	v_mov_b32_e32 v154, v44
	v_mov_b32_e32 v155, v37
	s_waitcnt vmcnt(3)
	v_mov_b32_e32 v146, v129
	s_waitcnt vmcnt(2)
	v_mov_b32_e32 v150, v136
	v_mov_b32_e32 v151, v139
	v_pk_mul_f32 v[150:151], v[140:141], v[150:151]
	v_mov_b32_e32 v140, v137
	v_mov_b32_e32 v141, v139
	v_mov_b32_e32 v142, v137
	v_mov_b32_e32 v143, v138
	v_pk_mul_f32 v[140:141], v[40:41], v[140:141]
	v_mov_b32_e32 v137, v138
	v_pk_fma_f32 v[140:141], v[32:33], v[136:137], v[140:141] neg_lo:[0,0,1] neg_hi:[0,0,1]
	v_pk_fma_f32 v[136:137], v[148:149], v[142:143], v[150:151]
	v_mov_b32_e32 v142, v42
	v_mov_b32_e32 v143, v35
	v_mov_b32_e32 v148, v128
	v_mov_b32_e32 v149, v131
	v_pk_mul_f32 v[148:149], v[142:143], v[148:149]
	v_mov_b32_e32 v142, v129
	v_mov_b32_e32 v143, v131
	v_mov_b32_e32 v147, v130
	v_mov_b32_e32 v138, v34
	v_mov_b32_e32 v139, v43
	v_pk_mul_f32 v[142:143], v[42:43], v[142:143]
	v_mov_b32_e32 v129, v130
	v_pk_fma_f32 v[142:143], v[34:35], v[128:129], v[142:143] neg_lo:[0,0,1] neg_hi:[0,0,1]
	v_pk_fma_f32 v[138:139], v[138:139], v[146:147], v[148:149]
	s_nop 0
	v_mov_b32_e32 v150, v36
	v_mov_b32_e32 v151, v45
	s_waitcnt vmcnt(1)
	v_mov_b32_e32 v152, v241
	s_waitcnt vmcnt(0)
	v_mov_b32_e32 v156, v244
	v_mov_b32_e32 v157, v247
	v_pk_mul_f32 v[154:155], v[154:155], v[156:157]
	v_mov_b32_e32 v156, v245
	v_mov_b32_e32 v148, v245
	v_mov_b32_e32 v149, v246
	v_pk_mul_f32 v[156:157], v[44:45], v[156:157]
	v_mov_b32_e32 v245, v246
	v_pk_fma_f32 v[246:247], v[36:37], v[244:245], v[156:157] neg_lo:[0,0,1] neg_hi:[0,0,1]
	v_pk_fma_f32 v[144:145], v[150:151], v[148:149], v[154:155]
	v_mov_b32_e32 v150, v46
	v_mov_b32_e32 v151, v39
	v_mov_b32_e32 v154, v240
	v_mov_b32_e32 v155, v243
	v_pk_mul_f32 v[154:155], v[150:151], v[154:155]
	v_mov_b32_e32 v150, v241
	v_mov_b32_e32 v151, v243
	v_mov_b32_e32 v153, v242
	v_mov_b32_e32 v148, v38
	v_mov_b32_e32 v149, v47
	v_pk_mul_f32 v[150:151], v[46:47], v[150:151]
	v_mov_b32_e32 v241, v242
	v_pk_fma_f32 v[150:151], v[38:39], v[240:241], v[150:151] neg_lo:[0,0,1] neg_hi:[0,0,1]
	v_pk_fma_f32 v[148:149], v[148:149], v[152:153], v[154:155]
	v_mov_b32_e32 v146, v246
	v_mov_b32_e32 v147, v247
.LBB0_220:
	s_and_b64 vcc, exec, s[2:3]
	v_mov_b32_e32 v152, v8
	v_mov_b32_e32 v153, v9
	v_mov_b32_e32 v154, v10
	v_mov_b32_e32 v155, v11
	v_mov_b32_e32 v160, v12
	v_mov_b32_e32 v161, v13
	v_mov_b32_e32 v128, v14
	v_mov_b32_e32 v129, v15
	v_mov_b32_e32 v156, v0
	v_mov_b32_e32 v157, v1
	v_mov_b32_e32 v158, v2
	v_mov_b32_e32 v159, v3
	v_mov_b32_e32 v162, v4
	v_mov_b32_e32 v163, v5
	v_mov_b32_e32 v130, v6
	v_mov_b32_e32 v131, v7
	v_readlane_b32 s62, v239, 60
	s_cbranch_vccnz .LBB0_222
	global_load_dwordx4 v[128:131], v[198:199], off offset:16
	global_load_dwordx4 v[152:155], v[198:199], off
	global_load_dwordx4 v[240:243], v[198:199], off offset:80
	global_load_dwordx4 v[244:247], v[198:199], off offset:64
	v_mov_b32_e32 v156, v8
	v_mov_b32_e32 v157, v1
	v_mov_b32_e32 v162, v0
	v_mov_b32_e32 v163, v9
	v_mov_b32_e32 v170, v12
	v_mov_b32_e32 v171, v5
	v_mov_b32_e32 v168, v4
	v_mov_b32_e32 v169, v13
	s_waitcnt vmcnt(3)
	v_mov_b32_e32 v160, v129
	s_waitcnt vmcnt(2)
	v_mov_b32_e32 v164, v152
	v_mov_b32_e32 v165, v155
	v_pk_mul_f32 v[164:165], v[156:157], v[164:165]
	v_mov_b32_e32 v156, v153
	v_mov_b32_e32 v157, v155
	v_mov_b32_e32 v158, v153
	v_mov_b32_e32 v159, v154
	v_pk_mul_f32 v[156:157], v[8:9], v[156:157]
	v_mov_b32_e32 v153, v154
	v_pk_fma_f32 v[156:157], v[0:1], v[152:153], v[156:157] neg_lo:[0,0,1] neg_hi:[0,0,1]
	v_pk_fma_f32 v[152:153], v[162:163], v[158:159], v[164:165]
	v_mov_b32_e32 v158, v10
	v_mov_b32_e32 v159, v3
	v_mov_b32_e32 v162, v128
	v_mov_b32_e32 v163, v131
	v_pk_mul_f32 v[162:163], v[158:159], v[162:163]
	v_mov_b32_e32 v158, v129
	v_mov_b32_e32 v159, v131
	v_mov_b32_e32 v161, v130
	v_mov_b32_e32 v154, v2
	v_mov_b32_e32 v155, v11
	v_pk_mul_f32 v[158:159], v[10:11], v[158:159]
	v_mov_b32_e32 v129, v130
	v_pk_fma_f32 v[158:159], v[2:3], v[128:129], v[158:159] neg_lo:[0,0,1] neg_hi:[0,0,1]
	v_pk_fma_f32 v[154:155], v[154:155], v[160:161], v[162:163]
	s_waitcnt vmcnt(1)
	v_mov_b32_e32 v166, v241
	s_waitcnt vmcnt(0)
	v_mov_b32_e32 v172, v244
	v_mov_b32_e32 v173, v247
	v_pk_mul_f32 v[170:171], v[170:171], v[172:173]
	v_mov_b32_e32 v172, v245
	v_mov_b32_e32 v164, v245
	v_mov_b32_e32 v165, v246
	v_pk_mul_f32 v[172:173], v[12:13], v[172:173]
	v_mov_b32_e32 v245, v246
	v_pk_fma_f32 v[246:247], v[4:5], v[244:245], v[172:173] neg_lo:[0,0,1] neg_hi:[0,0,1]
	v_pk_fma_f32 v[160:161], v[168:169], v[164:165], v[170:171]
	v_mov_b32_e32 v168, v14
	v_mov_b32_e32 v169, v7
	v_mov_b32_e32 v170, v240
	v_mov_b32_e32 v171, v243
	v_pk_mul_f32 v[168:169], v[168:169], v[170:171]
	v_mov_b32_e32 v170, v241
	v_mov_b32_e32 v167, v242
	v_mov_b32_e32 v164, v6
	v_mov_b32_e32 v165, v15
	v_pk_mul_f32 v[170:171], v[14:15], v[170:171]
	v_mov_b32_e32 v241, v242
	v_pk_fma_f32 v[242:243], v[6:7], v[240:241], v[170:171] neg_lo:[0,0,1] neg_hi:[0,0,1]
	v_pk_fma_f32 v[128:129], v[164:165], v[166:167], v[168:169]
	v_mov_b32_e32 v130, v242
	v_mov_b32_e32 v131, v243
	v_mov_b32_e32 v162, v246
	v_mov_b32_e32 v163, v247

.LBB0_1069:
	s_and_b32 s48, s45, 7
	s_lshl_b32 s49, s48, 2
	s_add_i32 s47, s49, s11
	v_or_b32_e32 v2, s47, v108
	v_lshl_add_u32 v0, v2, 6, v109
	s_ashr_i32 s30, s45, 7
	v_ashrrev_i32_e32 v1, 31, v0
	v_mad_i64_i32 v[102:103], s[12:13], s30, v130, v[0:1]
	v_readlane_b32 s72, v239, 32
	s_bfe_u32 s40, s45, 0x40003
	v_lshlrev_b64 v[0:1], 11, v[102:103]
	v_readlane_b32 s74, v239, 34
	v_readlane_b32 s75, v239, 35
	s_lshl_b32 s22, s40, 7
	s_lshl_b32 s46, s40, 6
	v_lshl_add_u64 v[0:1], s[74:75], 0, v[0:1]
	v_lshl_add_u64 v[0:1], v[0:1], 0, s[22:23]
	v_lshl_add_u64 v[0:1], v[0:1], 0, v[98:99]
	global_load_dwordx4 v[64:67], v[0:1], off
	global_load_dwordx4 v[68:71], v[0:1], off offset:32
	global_load_dwordx4 v[72:75], v[0:1], off offset:64
	global_load_dwordx4 v[76:79], v[0:1], off offset:96
	v_mad_i64_i32 v[0:1], s[12:13], s30, v130, v[92:93]
	s_mul_hi_i32 s13, s30, 0xfffffb00
	s_mulk_i32 s30, 0xfb00
	v_readlane_b32 s76, v239, 36
	v_readlane_b32 s77, v239, 37
	v_lshlrev_b64 v[4:5], 11, v[0:1]
	s_add_u32 s12, s46, s30
	v_lshl_add_u64 v[4:5], s[76:77], 0, v[4:5]
	s_addc_u32 s13, 0, s13
	v_lshl_add_u64 v[4:5], v[4:5], 0, s[22:23]
	v_lshl_add_u64 v[0:1], s[12:13], 0, v[0:1]
	v_lshl_add_u64 v[104:105], v[4:5], 0, v[100:101]
	v_mad_u64_u32 v[106:107], s[12:13], v0, s33, v[96:97]
	v_mad_i32_i24 v107, v1, s33, v107
	global_load_dwordx4 v[80:83], v[104:105], off
	global_load_dwordx4 v[84:87], v[106:107], off
	s_mov_b64 s[98:99], 0x20000
	v_lshl_add_u64 v[248:249], v[104:105], 0, s[98:99]
	global_load_dwordx4 v[240:243], v[248:249], off
	global_load_dwordx4 v[244:247], v[106:107], off offset:128
	v_med3_u32 v0, s49, 1, 25
	v_readlane_b32 s73, v239, 33
	v_readfirstlane_b32 s50, v0
	v_readlane_b32 s78, v239, 38
	v_readlane_b32 s79, v239, 39
	s_waitcnt vmcnt(63) expcnt(7) lgkmcnt(15)
	s_barrier
	s_and_saveexec_b64 s[12:13], s[0:1]
	s_cbranch_execz .LBB0_1082
	s_mov_b64 s[38:39], -1
	v_mov_b32_e32 v0, v90
	s_and_saveexec_b64 s[30:31], s[2:3]
	s_cbranch_execz .LBB0_1079
	s_mulk_i32 s40, 0x744
	s_add_u32 s38, s56, s40
	s_addc_u32 s39, s57, 0
	v_mov_b32_e32 v5, 0
	v_mov_b64_e32 v[0:1], v[90:91]
	s_and_saveexec_b64 s[40:41], s[4:5]
	s_cbranch_execz .LBB0_1075
	s_mov_b32 s22, 0
	s_mov_b64 s[42:43], 0
	v_mov_b32_e32 v3, v127
	v_mov_b32_e32 v4, v126
	v_mov_b64_e32 v[0:1], v[90:91]

.LBB0_1084:
	s_bitcmp1_b32 s41, 0
	s_cselect_b32 s40, 0x4200, 0
	s_add_i32 s39, s41, 1
	v_add3_u32 v32, s40, v111, v112
	v_add_u32_e32 v248, s40, v110
	v_add3_u32 v248, v248, v94, s34
	s_cmp_ge_i32 s39, s38
	s_cselect_b64 s[30:31], -1, 0
	s_cbranch_scc1 .Lna_last
	s_waitcnt vmcnt(2)
	s_branch .Lna_w
.Lna_last:
	s_waitcnt vmcnt(0)
.Lna_w:
	s_bitcmp1_b32 s41, 0
	s_cbranch_scc1 .Lna_wodd
	ds_write_b128 v32, v[80:83]
	ds_write2_b64 v248, v[84:85], v[86:87] offset1:1
	s_branch .Lna_wd
.Lna_wodd:
	ds_write_b128 v32, v[240:243]
	ds_write2_b64 v248, v[244:245], v[246:247] offset1:1
.Lna_wd:
	s_and_b64 vcc, exec, s[30:31]
	s_waitcnt lgkmcnt(0)
	s_barrier
	s_add_i32 s98, s41, 2
	s_cmp_ge_i32 s98, s38
	s_cbranch_scc1 .LBB0_1086
	s_cmp_gt_u32 s41, 1
	s_cselect_b32 s12, s22, 0
	s_add_i32 s12, s12, s41
	s_lshl_b32 s12, s12, 6
	s_add_i32 s12, s12, 0x80
	s_ashr_i32 s13, s12, 31
	s_lshl_b64 s[42:43], s[12:13], 11
	v_lshl_add_u64 v[32:33], v[104:105], 0, s[42:43]
	v_lshl_add_u64 v[248:249], s[12:13], 1, v[106:107]
	s_bitcmp1_b32 s41, 0
	s_cbranch_scc1 .Lna_lodd
	global_load_dwordx4 v[80:83], v[32:33], off
	global_load_dwordx4 v[84:87], v[248:249], off
	s_branch .LBB0_1086
.Lna_lodd:
	global_load_dwordx4 v[240:243], v[32:33], off
	global_load_dwordx4 v[244:247], v[248:249], off
